# attention: next item's Q loads issued behind the epilogue's gate loads (registers free there), epilogue vmcnt ladder +8, next prologue skips Q loads
# speedup vs baseline: 1.0106x; 1.0002x over previous
; DI int v_st(int k, int c) { const int kk = (k & ~0xC) | ((k & 4) << 1) | ((k & 8) >> 1); return ((kk >> 3) * 4 + (c >> 5)) * 512 + ((kk & 7) * 32 + (c & 31)) * 2; }
; DI int v_rd_base(int lane) { return ((lane & 3) << 3) | (((lane >> 2) & 3) << 6) | (((lane >> 4) & 1) << 5) | (((lane >> 5) & 1) << 8); }
; DI void attn_item(const bf16_t* __restrict__ Qw_, const bf16_t* __restrict__ Kh, const bf16_t* __restrict__ Vh, const bf16_t* Gw, bf16_t* Ow,
;                   int NT, int kt0, int qw, float sinkv, char* lds) {
;     const int tid = threadIdx.x, wid = __builtin_amdgcn_readfirstlane(tid >> 6), lane = tid & 63, r32 = lane & 31, hi = lane >> 5;
;     char* V_lds = lds; char* K_lds = lds + 2 * SHM_V;
;     float* wsp = (float*)(lds + 2 * SHM_V + 2 * SHM_K) + wid * 64; float* li_l = wsp; float* al_l = wsp + 32;
;     float m_reg = sinkv * (1.f / SCALE), l_reg = 1.f; f32x16 o[4]; bf16x8 qr[8];
; #pragma unroll
;     for (int d = 0; d < 4; ++d)
; #pragma unroll
;         for (int r = 0; r < 16; ++r) o[d][r] = 0.f;
;     const bf16_t* Qw = Qw_ + (size_t)r32 * LDK + hi * 8;
; #pragma unroll
;     for (int d0 = 0; d0 < 8; ++d0) qr[d0] = *(const bf16x8*)(Qw + d0 * 16);
;     const int sr = tid >> 4, sc = (tid & 15) * 8, vst0 = v_st(sr, sc), vst1 = v_st(32 + sr, sc);
;     const int vb0 = (int)(uintptr_t)V_lds + v_rd_base(lane);
;     struct { bf16x8 vs0, vs1, ks0, ks1; } sr_[2];
; DI void phase_att(const Params& p, unsigned char* shm) {
;     const int wid = __builtin_amdgcn_readfirstlane(threadIdx.x >> 6);
;     const bf16_t* Z = (const bf16_t*)(p.ws + WS_ZQKV); const bf16_t* GA = (const bf16_t*)(p.ws + WS_ZGA); bf16_t* YB = (bf16_t*)(p.ws + WS_YB);
;     for (int it = blockIdx.x; it < 1024; it += gridDim.x) {
;         const int hp = it & 1, g = (it >> 1) & 3, n = it >> 3;
;         const int head = g * 4 + hp * 2 + (wid >> 2), qw = 32 * (wid & 3);
;         const int kfirst = n == 0 ? 0 : (n - 1) * 128, NT = (n == 0 || n == 127) ? 4 : 6, kt0 = kfirst - n * 128;
;         __syncthreads();
.LBB0_234:
	s_bitcmp0_b32 s4, 1
	s_cbranch_scc1 .LBB0_266
	s_cmpk_gt_i32 s2, 0x3ff
	v_readfirstlane_b32 s6, v202
	s_cbranch_scc1 .LBB0_265
	v_lshrrev_b32_e32 v180, 4, v202
	s_load_dwordx2 s[4:5], s[0:1], 0x80
	s_load_dwordx2 s[8:9], s[0:1], 0x50
	s_waitcnt vmcnt(0)
	v_add_u32_e32 v10, 32, v180
	v_and_b32_e32 v5, 48, v180
	v_lshrrev_b32_e32 v6, 3, v202
	v_and_b32_e32 v11, 0x70, v10
	v_lshlrev_b32_e32 v12, 1, v10
	v_lshlrev_b32_e32 v3, 3, v202
	v_and_or_b32 v5, v6, 8, v5
	v_and_or_b32 v11, v12, 8, v11
	v_and_b32_e32 v4, 0x78, v3
	v_lshrrev_b32_e32 v5, 1, v5
	v_bfe_u32 v6, v3, 5, 2
	v_bfe_u32 v7, v202, 4, 2
	v_lshrrev_b32_e32 v11, 1, v11
	s_waitcnt lgkmcnt(0)
	s_add_u32 s11, s4, 0x8000000
	v_or_b32_e32 v5, v5, v6
	v_and_or_b32 v7, v203, 4, v7
	v_lshlrev_b32_e32 v8, 1, v4
	v_or_b32_e32 v6, v11, v6
	s_addc_u32 s22, s5, 0
	v_lshlrev_b32_e32 v5, 9, v5
	v_lshlrev_b32_e32 v7, 6, v7
	v_and_b32_e32 v9, 48, v8
	v_lshlrev_b32_e32 v6, 9, v6
	s_add_u32 s23, s4, 0xe000000
	v_or3_b32 v5, v5, v7, v9
	v_or3_b32 v7, v6, v7, v9
	v_lshlrev_b32_e32 v9, 4, v202
	v_lshlrev_b32_e32 v11, 1, v202
	s_addc_u32 s30, s5, 0
	s_lshr_b32 s31, s6, 8
	s_lshr_b32 s6, s6, 1
	v_bfe_u32 v0, v202, 5, 1
	v_and_b32_e32 v6, 0xc0, v9
	v_and_b32_e32 v11, 32, v11
	v_and_b32_e32 v3, 0x118, v3
	v_and_b32_e32 v188, 31, v202
	s_and_b32 s34, s6, 0x60
	v_or3_b32 v3, v11, v6, v3
	v_lshlrev_b32_e32 v11, 8, v180
	v_and_b32_e32 v12, 0x70, v202
	v_lshlrev_b32_e32 v10, 8, v10
	v_lshlrev_b32_e32 v191, 4, v0
	s_cmp_lg_u32 0, -1
	v_bitop3_b32 v11, v8, v11, v12 bitop3:0xde
	v_bitop3_b32 v13, v8, v10, v12 bitop3:0xde
	v_lshlrev_b32_e32 v8, 8, v188
	v_and_b32_e32 v9, 0x70, v9
	v_or_b32_e32 v10, 32, v191
	s_cselect_b32 s10, 0, 0
	v_bitop3_b32 v18, v10, v8, v9 bitop3:0xde
	v_or_b32_e32 v10, 64, v191
	v_add_u32_e32 v190, s10, v3
	v_bitop3_b32 v19, v10, v8, v9 bitop3:0xde
	v_or_b32_e32 v10, 0x60, v191
	v_lshlrev_b32_e32 v193, 2, v0
	s_addk_i32 s10, 0x4000
	v_lshlrev_b32_e32 v2, 3, v0
	v_bitop3_b32 v20, v10, v8, v9 bitop3:0xde
	v_or_b32_e32 v10, 0x80, v191
	v_add_u32_e32 v194, s10, v3
	v_mul_u32_u24_e32 v196, 0x440, v0
	v_or_b32_e32 v0, 1, v193
	s_movk_i32 s39, 0x110
	v_mov_b32_e32 v3, 0x990
	v_bitop3_b32 v21, v10, v8, v9 bitop3:0xde
	v_or_b32_e32 v10, 0xa0, v191
	v_mul_u32_u24_e32 v197, 0x110, v0
	v_mad_u32_u24 v198, v0, s39, v3
	v_sub_u32_e32 v0, v193, v188
	v_mul_u32_u24_e32 v6, 0xc00, v180
	v_bitop3_b32 v22, v10, v8, v9 bitop3:0xde
	v_or_b32_e32 v10, 0xc0, v191
	v_subrev_u32_e32 v199, s34, v0
	v_and_b32_e32 v0, 15, v202
	v_mov_b32_e32 v1, 0
	v_or_b32_e32 v4, v6, v4
	v_bitop3_b32 v23, v10, v8, v9 bitop3:0xde
	v_or_b32_e32 v10, 0xe0, v191
	v_lshlrev_b32_e32 v0, 4, v0
	v_and_b32_e32 v189, 63, v202
	v_add_u32_e32 v6, 0x18000, v4
	v_bitop3_b32 v15, v191, v8, v9 bitop3:0xde
	v_bitop3_b32 v9, v10, v8, v9 bitop3:0xde
	v_or_b32_e32 v192, s34, v188
	v_add_u32_e32 v8, 0x30000, v4
	v_add_u32_e32 v10, 0x48000, v4
	v_add_u32_e32 v12, 0x78000, v4
	v_add_u32_e32 v14, 0x60000, v4
	v_lshl_add_u64 v[16:17], s[4:5], 0, v[0:1]
	s_mov_b64 s[4:5], 0x81b1400
	s_movk_i32 s35, 0x1800
	v_mul_u32_u24_e32 v178, 0x1800, v188
	v_mov_b32_e32 v179, v1
	s_mov_b32 s36, 0x18000
	s_or_b32 s37, s6, 0xffffff9f
	v_cmp_gt_u32_e64 s[6:7], 32, v189
	s_movk_i32 s38, 0x4000
	v_sub_u32_e32 v195, v193, v192
	s_sub_i32 s40, 0, s34
	v_lshl_add_u64 v[182:183], v[16:17], 0, s[4:5]
	v_mov_b32_e32 v181, v1
	v_lshlrev_b32_e32 v184, 1, v2
	v_lshlrev_b32_e32 v200, 1, v4
	v_lshlrev_b32_e32 v201, 1, v6
	s_movk_i32 s41, 0x101
	s_mov_b32 s42, 0x10000
	s_mov_b32 s43, 0x413504f3
	s_mov_b32 s44, 0x42b504f3
	s_mov_b32 s10, 0x3e0293ee
	v_lshlrev_b32_e32 v204, 1, v8
	v_lshlrev_b32_e32 v205, 1, v10
	v_lshlrev_b32_e32 v206, 1, v12
	v_lshlrev_b32_e32 v207, 1, v14
	s_mov_b32 s45, 0xfff70000
	s_mov_b32 s46, 0xfffa0000
	s_mov_b64 s[12:13], 0xc0000
	s_mov_b32 s47, 0x8000
	s_mov_b32 s48, 0xc000
	s_mov_b32 s49, 0x14000
	s_mov_b32 s50, 0x1c000
	v_mov_b32_e32 v185, v1
	v_add_u32_e32 v208, 0, v5
	v_add_u32_e32 v209, 0, v7
	v_add_u32_e32 v210, 0, v11
	v_add_u32_e32 v211, 0, v13
	v_add_u32_e32 v212, 0, v15
	v_add_u32_e32 v213, 0, v18
	v_add_u32_e32 v214, 0, v19
	v_add_u32_e32 v215, 0, v20
	v_add_u32_e32 v216, 0, v21
	v_add_u32_e32 v217, 0, v22
	v_add_u32_e32 v218, 0, v23
	v_add_u32_e32 v219, 0, v9
	v_mov_b32_e32 v220, 0xf149f2ca
	s_mov_b32 s71, 0
	s_mov_b32 s51, s2
	s_branch .LBB0_238
; DI unsigned short f2bf(float f) { return (unsigned short)(cvtpk(f, f) & 0xffffu); }
; DI int crow(int r, int hi) { return (r & 3) + 8 * (r >> 2) + 4 * hi; }
; DI void attn_item(const bf16_t* __restrict__ Qw_, const bf16_t* __restrict__ Kh, const bf16_t* __restrict__ Vh, const bf16_t* Gw, bf16_t* Ow,
;                   int NT, int kt0, int qw, float sinkv, char* lds) {
;     ...
;     int lane2 = threadIdx.x & 63; asm volatile("" : "+v"(lane2));
;     const int ec = lane2 & 15, er = lane2 >> 4;
;     if (hi == 0) li_l[r32] = l_reg; asm volatile("s_waitcnt lgkmcnt(0)" ::: "memory");
;     bf16_t* OT = (bf16_t*)(lds + 67584 + wid * 8704);
; #pragma unroll
;     for (int r = 0; r < 16; ++r) { const int orow = crow(r, hi); const float rl = __builtin_amdgcn_rcpf(li_l[orow]);
; #pragma unroll
;         for (int d0 = 0; d0 < 4; ++d0) OT[orow * 136 + d0 * 32 + r32] = f2bf(o[d0][r] * rl); }
.LBB0_237:
	s_or_b64 exec, exec, s[4:5]
	s_waitcnt lgkmcnt(0)
	v_lshl_add_u32 v0, v193, 2, s54
	s_lshl_b64 s[4:5], s[14:15], 12
	ds_read_b32 v67, v0
	s_add_u32 s4, s23, s4
	s_addc_u32 s5, s30, s5
	s_lshl_b32 s14, s53, 1
	s_add_u32 s4, s4, s14
	s_addc_u32 s5, s5, 0
	s_lshr_b32 s14, s52, 6
	s_mulk_i32 s14, 0x2200
	s_waitcnt lgkmcnt(0)
	v_rcp_f32_e32 v67, v67
	s_add_i32 s14, s14, 0
	s_add_i32 s14, s14, 0x10800
	v_lshl_add_u32 v68, v188, 1, s14
	v_add_u32_e32 v69, v68, v196
	v_mul_f32_e32 v50, v50, v67
	v_mul_f32_e32 v34, v34, v67
	v_mul_f32_e32 v18, v18, v67
	v_cvt_pk_bf16_f32 v50, v50, v50
	ds_write_b16 v69, v50
	v_cvt_pk_bf16_f32 v34, v34, v34
	ds_write_b16 v69, v34 offset:64
	v_cvt_pk_bf16_f32 v18, v18, v18
	v_mul_f32_e32 v2, v2, v67
	ds_write_b16 v69, v18 offset:128
	v_cvt_pk_bf16_f32 v2, v2, v2
	ds_read_b32 v18, v0 offset:4
	ds_write_b16 v69, v2 offset:192
	v_add_u32_e32 v2, v68, v197
	s_waitcnt lgkmcnt(1)
	v_rcp_f32_e32 v18, v18
	s_nop 0
	v_mul_f32_e32 v34, v51, v18
	v_cvt_pk_bf16_f32 v34, v34, v34
	ds_write_b16 v2, v34
	v_mul_f32_e32 v34, v35, v18
	v_mul_f32_e32 v19, v19, v18
	v_mul_f32_e32 v3, v3, v18
	v_cvt_pk_bf16_f32 v34, v34, v34
	ds_write_b16 v2, v34 offset:64
	v_cvt_pk_bf16_f32 v19, v19, v19
	ds_write_b16 v2, v19 offset:128
	v_cvt_pk_bf16_f32 v3, v3, v3
	ds_read_b32 v18, v0 offset:8
	ds_write_b16 v2, v3 offset:192
	s_waitcnt lgkmcnt(1)
	v_rcp_f32_e32 v18, v18
	s_nop 0
	v_mul_f32_e32 v3, v52, v18
	v_cvt_pk_bf16_f32 v3, v3, v3
	ds_write_b16 v2, v3 offset:272
	v_mul_f32_e32 v3, v36, v18
	v_cvt_pk_bf16_f32 v3, v3, v3
	ds_write_b16 v2, v3 offset:336
	v_mul_f32_e32 v3, v20, v18
	v_cvt_pk_bf16_f32 v3, v3, v3
	ds_write_b16 v2, v3 offset:400
	v_mul_f32_e32 v3, v4, v18
	v_cvt_pk_bf16_f32 v3, v3, v3
	ds_read_b32 v4, v0 offset:12
	ds_write_b16 v2, v3 offset:464
	s_waitcnt lgkmcnt(1)
	v_rcp_f32_e32 v4, v4
	s_nop 0
	v_mul_f32_e32 v3, v53, v4
	v_cvt_pk_bf16_f32 v3, v3, v3
	ds_write_b16 v2, v3 offset:544
	v_mul_f32_e32 v3, v37, v4
	v_cvt_pk_bf16_f32 v3, v3, v3
	ds_write_b16 v2, v3 offset:608
	v_mul_f32_e32 v3, v21, v4
	v_cvt_pk_bf16_f32 v3, v3, v3
	ds_write_b16 v2, v3 offset:672
	v_mul_f32_e32 v3, v5, v4
	v_cvt_pk_bf16_f32 v3, v3, v3
	ds_read_b32 v4, v0 offset:32
	ds_write_b16 v2, v3 offset:736
	s_waitcnt lgkmcnt(1)
	v_rcp_f32_e32 v4, v4
	s_nop 0
	v_mul_f32_e32 v3, v54, v4
	v_cvt_pk_bf16_f32 v3, v3, v3
	ds_write_b16 v2, v3 offset:1904
	v_mul_f32_e32 v3, v38, v4
	v_cvt_pk_bf16_f32 v3, v3, v3
	ds_write_b16 v2, v3 offset:1968
	v_mul_f32_e32 v3, v22, v4
	v_cvt_pk_bf16_f32 v3, v3, v3
	ds_write_b16 v2, v3 offset:2032
	v_mul_f32_e32 v3, v6, v4
	v_cvt_pk_bf16_f32 v3, v3, v3
	ds_read_b32 v4, v0 offset:36
	ds_write_b16 v2, v3 offset:2096
	s_waitcnt lgkmcnt(1)
	v_rcp_f32_e32 v4, v4
	s_nop 0
	v_mul_f32_e32 v3, v55, v4
	v_cvt_pk_bf16_f32 v3, v3, v3
	ds_write_b16 v2, v3 offset:2176
	v_mul_f32_e32 v3, v39, v4
	v_cvt_pk_bf16_f32 v3, v3, v3
	ds_write_b16 v2, v3 offset:2240
	v_mul_f32_e32 v3, v23, v4
	v_cvt_pk_bf16_f32 v3, v3, v3
	ds_write_b16 v2, v3 offset:2304
	v_mul_f32_e32 v3, v7, v4
	v_cvt_pk_bf16_f32 v3, v3, v3
	ds_read_b32 v4, v0 offset:40
	ds_write_b16 v2, v3 offset:2368
	v_add_u32_e32 v3, v68, v198
	s_waitcnt lgkmcnt(1)
	v_rcp_f32_e32 v4, v4
	s_nop 0
	v_mul_f32_e32 v5, v56, v4
	v_cvt_pk_bf16_f32 v5, v5, v5
	ds_write_b16 v2, v5 offset:2448
	v_mul_f32_e32 v2, v40, v4
	v_cvt_pk_bf16_f32 v2, v2, v2
	ds_write_b16 v3, v2 offset:64
	v_mul_f32_e32 v2, v24, v4
	v_cvt_pk_bf16_f32 v2, v2, v2
	ds_write_b16 v3, v2 offset:128
	v_mul_f32_e32 v2, v8, v4
	v_cvt_pk_bf16_f32 v2, v2, v2
	ds_read_b32 v4, v0 offset:44
	ds_write_b16 v3, v2 offset:192
	s_waitcnt lgkmcnt(1)
	v_rcp_f32_e32 v4, v4
	s_nop 0
	v_mul_f32_e32 v2, v57, v4
	v_cvt_pk_bf16_f32 v2, v2, v2
	ds_write_b16 v3, v2 offset:272
	v_mul_f32_e32 v2, v41, v4
	v_cvt_pk_bf16_f32 v2, v2, v2
	ds_write_b16 v3, v2 offset:336
	v_mul_f32_e32 v2, v25, v4
	v_cvt_pk_bf16_f32 v2, v2, v2
	ds_write_b16 v3, v2 offset:400
	v_mul_f32_e32 v2, v9, v4
	v_cvt_pk_bf16_f32 v2, v2, v2
	ds_read_b32 v4, v0 offset:64
	ds_write_b16 v3, v2 offset:464
	s_waitcnt lgkmcnt(1)
	v_rcp_f32_e32 v4, v4
	s_nop 0
	v_mul_f32_e32 v2, v58, v4
	v_cvt_pk_bf16_f32 v2, v2, v2
	ds_write_b16 v3, v2 offset:1632
	v_mul_f32_e32 v2, v42, v4
	v_cvt_pk_bf16_f32 v2, v2, v2
	ds_write_b16 v3, v2 offset:1696
	v_mul_f32_e32 v2, v26, v4
	v_cvt_pk_bf16_f32 v2, v2, v2
	ds_write_b16 v3, v2 offset:1760
	v_mul_f32_e32 v2, v10, v4
	v_cvt_pk_bf16_f32 v2, v2, v2
	ds_read_b32 v4, v0 offset:68
	ds_write_b16 v3, v2 offset:1824
	s_waitcnt lgkmcnt(1)
	v_rcp_f32_e32 v4, v4
	s_nop 0
	v_mul_f32_e32 v2, v59, v4
	v_cvt_pk_bf16_f32 v2, v2, v2
	ds_write_b16 v3, v2 offset:1904
	v_mul_f32_e32 v2, v43, v4
	v_cvt_pk_bf16_f32 v2, v2, v2
	ds_write_b16 v3, v2 offset:1968
	v_mul_f32_e32 v2, v27, v4
	v_cvt_pk_bf16_f32 v2, v2, v2
	ds_write_b16 v3, v2 offset:2032
	v_mul_f32_e32 v2, v11, v4
	v_cvt_pk_bf16_f32 v2, v2, v2
	ds_read_b32 v4, v0 offset:72
	ds_write_b16 v3, v2 offset:2096
	s_waitcnt lgkmcnt(1)
	v_rcp_f32_e32 v4, v4
	s_nop 0
	v_mul_f32_e32 v2, v60, v4
	v_cvt_pk_bf16_f32 v2, v2, v2
	ds_write_b16 v3, v2 offset:2176
	v_mul_f32_e32 v2, v44, v4
	v_cvt_pk_bf16_f32 v2, v2, v2
	ds_write_b16 v3, v2 offset:2240
	v_mul_f32_e32 v2, v28, v4
	v_cvt_pk_bf16_f32 v2, v2, v2
	ds_write_b16 v3, v2 offset:2304
	v_mul_f32_e32 v2, v12, v4
	v_cvt_pk_bf16_f32 v2, v2, v2
	ds_read_b32 v4, v0 offset:76
	ds_write_b16 v3, v2 offset:2368
	s_waitcnt lgkmcnt(1)
	v_rcp_f32_e32 v4, v4
	s_nop 0
	v_mul_f32_e32 v2, v61, v4
	v_cvt_pk_bf16_f32 v2, v2, v2
	ds_write_b16 v3, v2 offset:2448
	v_mul_f32_e32 v2, v45, v4
	v_cvt_pk_bf16_f32 v2, v2, v2
	ds_write_b16 v3, v2 offset:2512
	v_mul_f32_e32 v2, v29, v4
	v_cvt_pk_bf16_f32 v2, v2, v2
	ds_write_b16 v3, v2 offset:2576
	v_mul_f32_e32 v2, v13, v4
	v_cvt_pk_bf16_f32 v2, v2, v2
	ds_read_b32 v4, v0 offset:96
	ds_write_b16 v3, v2 offset:2640
	s_waitcnt lgkmcnt(1)
; DI unsigned cvtpk(float lo, float hi) { unsigned r; asm volatile("v_cvt_pk_bf16_f32 %0, %1, %2" : "=v"(r) : "v"(lo), "v"(hi)); return r; }
; DI float bflo(unsigned w) { return __uint_as_float(w << 16); }
; DI float bfhi(unsigned w) { return __uint_as_float(w & 0xffff0000u); }
; DI float sigm(float x) { return rcpf_(1.f + ex2(-x * LOG2E)); }
; DI void attn_item(const bf16_t* __restrict__ Qw_, const bf16_t* __restrict__ Kh, const bf16_t* __restrict__ Vh, const bf16_t* Gw, bf16_t* Ow,
;                   int NT, int kt0, int qw, float sinkv, char* lds) {
;     ...
;     const bf16_t* Qw = Qw_ + (size_t)r32 * LDK + hi * 8;
; #pragma unroll
;     for (int d0 = 0; d0 < 8; ++d0) qr[d0] = *(const bf16x8*)(Qw + d0 * 16);
;     ...
;     u32x4 gv[8];
; #pragma unroll
;     for (int k = 0; k < 8; ++k) gv[k] = __builtin_nontemporal_load((const u32x4*)(Gw + (size_t)(er + 4 * k) * 2048 + ec * 8));
;     asm volatile("s_waitcnt lgkmcnt(0)" ::: "memory");
; #pragma unroll
;     for (int k = 0; k < 8; ++k) {
;         const u32x4 ov = *(const u32x4*)(OT + (er + 4 * k) * 136 + ec * 8); u32x4 w;
; #pragma unroll
;         for (int i = 0; i < 4; ++i) { const float g0 = bflo(gv[k][i]), g1 = bfhi(gv[k][i]); w[i] = cvtpk(bflo(ov[i]) * g0 * sigm(g0), bfhi(ov[i]) * g1 * sigm(g1)); }
;         __builtin_nontemporal_store(w, (u32x4*)(Ow + (size_t)(er + 4 * k) * 2048 + ec * 8));
;     }
; DI void phase_att(const Params& p, unsigned char* shm) {
;     ...
;     for (int it = blockIdx.x; it < 1024; it += gridDim.x) {
;         const int hp = it & 1, g = (it >> 1) & 3, n = it >> 3;
;         const int head = g * 4 + hp * 2 + (wid >> 2), qw = 32 * (wid & 3);
	v_rcp_f32_e32 v4, v4
	s_nop 0
	v_mul_f32_e32 v2, v62, v4
	v_cvt_pk_bf16_f32 v2, v2, v2
	ds_write_b16 v3, v2 offset:3808
	v_mul_f32_e32 v2, v46, v4
	v_cvt_pk_bf16_f32 v2, v2, v2
	ds_write_b16 v3, v2 offset:3872
	v_mul_f32_e32 v2, v30, v4
	v_cvt_pk_bf16_f32 v2, v2, v2
	ds_write_b16 v3, v2 offset:3936
	v_mul_f32_e32 v2, v14, v4
	v_cvt_pk_bf16_f32 v2, v2, v2
	ds_read_b32 v4, v0 offset:100
	ds_write_b16 v3, v2 offset:4000
	s_waitcnt lgkmcnt(1)
	v_rcp_f32_e32 v4, v4
	s_nop 0
	v_mul_f32_e32 v2, v63, v4
	v_cvt_pk_bf16_f32 v2, v2, v2
	ds_write_b16 v3, v2 offset:4080
	v_mul_f32_e32 v2, v47, v4
	v_cvt_pk_bf16_f32 v2, v2, v2
	ds_write_b16 v3, v2 offset:4144
	v_mul_f32_e32 v2, v31, v4
	v_cvt_pk_bf16_f32 v2, v2, v2
	ds_write_b16 v3, v2 offset:4208
	v_mul_f32_e32 v2, v15, v4
	v_cvt_pk_bf16_f32 v2, v2, v2
	ds_read_b32 v4, v0 offset:104
	ds_write_b16 v3, v2 offset:4272
	s_waitcnt lgkmcnt(1)
	v_rcp_f32_e32 v4, v4
	s_nop 0
	v_mul_f32_e32 v2, v64, v4
	v_cvt_pk_bf16_f32 v2, v2, v2
	ds_write_b16 v3, v2 offset:4352
	v_mul_f32_e32 v2, v48, v4
	v_cvt_pk_bf16_f32 v2, v2, v2
	ds_write_b16 v3, v2 offset:4416
	v_mul_f32_e32 v2, v32, v4
	v_cvt_pk_bf16_f32 v2, v2, v2
	ds_write_b16 v3, v2 offset:4480
	v_mul_f32_e32 v2, v16, v4
	v_cvt_pk_bf16_f32 v4, v2, v2
	ds_read_b32 v0, v0 offset:108
	ds_write_b16 v3, v4 offset:4544
	v_ashrrev_i32_e32 v2, 4, v66
	s_waitcnt lgkmcnt(1)
	v_rcp_f32_e32 v0, v0
	s_nop 0
	v_mul_f32_e32 v4, v65, v0
	v_cvt_pk_bf16_f32 v4, v4, v4
	ds_write_b16 v3, v4 offset:4624
	v_mul_f32_e32 v4, v49, v0
	v_cvt_pk_bf16_f32 v4, v4, v4
	ds_write_b16 v3, v4 offset:4688
	v_mul_f32_e32 v4, v33, v0
	v_mul_f32_e32 v0, v17, v0
	v_cvt_pk_bf16_f32 v4, v4, v4
	ds_write_b16 v3, v4 offset:4752
	v_cvt_pk_bf16_f32 v0, v0, v0
	ds_write_b16 v3, v0 offset:4816
	v_lshlrev_b32_e32 v0, 4, v66
	v_and_b32_e32 v0, 0xf0, v0
	v_ashrrev_i32_e32 v3, 31, v2
	v_lshl_add_u64 v[4:5], s[4:5], 0, v[0:1]
	v_lshlrev_b64 v[6:7], 12, v[2:3]
	v_lshl_add_u64 v[50:51], v[4:5], 0, v[6:7]
	global_load_dwordx4 v[38:41], v[50:51], off nt
	v_add_co_u32_e32 v52, vcc, s38, v50
	v_mul_lo_u32 v2, v2, s39
	s_nop 0
	v_addc_co_u32_e32 v53, vcc, 0, v51, vcc
	v_add_co_u32_e32 v36, vcc, s47, v50
	v_add3_u32 v0, s14, v0, v2
	s_nop 0
	v_addc_co_u32_e32 v37, vcc, 0, v51, vcc
	v_add_co_u32_e32 v34, vcc, s48, v50
	s_add_i32 s51, s51, s24
	s_nop 0
	v_addc_co_u32_e32 v35, vcc, 0, v51, vcc
	v_add_co_u32_e32 v32, vcc, s42, v50
	s_cmpk_lt_i32 s51, 0x400
	s_nop 0
	v_addc_co_u32_e32 v33, vcc, 0, v51, vcc
	v_add_co_u32_e32 v30, vcc, s49, v50
	s_waitcnt vmcnt(0)
	v_lshlrev_b32_e32 v57, 16, v38
	v_addc_co_u32_e32 v31, vcc, 0, v51, vcc
	v_add_co_u32_e32 v28, vcc, s36, v50
	v_and_b32_e32 v38, 0xffff0000, v38
	s_nop 0
	v_addc_co_u32_e32 v29, vcc, 0, v51, vcc
	v_add_co_u32_e32 v26, vcc, s50, v50
	v_lshlrev_b32_e32 v58, 16, v39
	s_nop 0
	v_addc_co_u32_e32 v27, vcc, 0, v51, vcc
	global_load_dwordx4 v[42:45], v[52:53], off nt
	global_load_dwordx4 v[22:25], v[36:37], off nt
	global_load_dwordx4 v[18:21], v[34:35], off nt
	global_load_dwordx4 v[14:17], v[32:33], off nt
	global_load_dwordx4 v[10:13], v[30:31], off nt
	global_load_dwordx4 v[6:9], v[28:29], off nt
	global_load_dwordx4 v[2:5], v[26:27], off nt
	s_cselect_b32 s60, 0, s24
	s_sub_i32 s60, s51, s60
	s_lshl_b32 s61, s60, 1
	s_and_b32 s61, s61, 2
	s_bfe_u32 s62, s60, 0x20001
	s_lshl_b32 s63, s62, 2
	s_add_i32 s61, s61, s31
	s_add_i32 s61, s61, s63
	s_ashr_i32 s63, s60, 3
	s_lshl_b32 s63, s63, 7
	s_or_b32 s64, s63, s34
	s_mul_i32 s65, s64, 0x1800
	s_mul_hi_i32 s66, s64, 0x1800
	s_add_u32 s65, s11, s65
	s_addc_u32 s66, s22, s66
	s_lshl_b32 s61, s61, 8
	s_add_u32 s68, s65, s61
	s_addc_u32 s69, s66, 0
	v_lshl_add_u64 v[60:61], s[68:69], 0, v[178:179]
	v_lshl_add_u64 v[60:61], v[60:61], 0, v[184:185]
	global_load_dwordx4 v[126:129], v[60:61], off
	global_load_dwordx4 v[122:125], v[60:61], off offset:32
	global_load_dwordx4 v[118:121], v[60:61], off offset:64
	global_load_dwordx4 v[114:117], v[60:61], off offset:96
	global_load_dwordx4 v[110:113], v[60:61], off offset:128
	global_load_dwordx4 v[106:109], v[60:61], off offset:160
	global_load_dwordx4 v[102:105], v[60:61], off offset:192
	global_load_dwordx4 v[98:101], v[60:61], off offset:224
	s_mov_b32 s71, 1
	s_cmpk_lt_i32 s51, 0x400
	s_waitcnt lgkmcnt(0)
	ds_read_b128 v[46:49], v0
	v_and_b32_e32 v39, 0xffff0000, v39
	v_lshlrev_b32_e32 v59, 16, v40
	v_and_b32_e32 v40, 0xffff0000, v40
	s_waitcnt lgkmcnt(0)
	v_lshlrev_b32_e32 v54, 16, v46
	v_and_b32_e32 v46, 0xffff0000, v46
	v_lshlrev_b32_e32 v55, 16, v47
	v_and_b32_e32 v47, 0xffff0000, v47
	v_mul_f32_e32 v46, v46, v38
	v_mul_f32_e32 v38, 0xbfb8aa3b, v38
	v_mul_f32_e32 v55, v55, v58
	v_mul_f32_e32 v58, 0xbfb8aa3b, v58
	v_mul_f32_e32 v47, v47, v39
	v_mul_f32_e32 v39, 0xbfb8aa3b, v39
	v_lshlrev_b32_e32 v56, 16, v48
	v_and_b32_e32 v48, 0xffff0000, v48
	v_mul_f32_e32 v54, v54, v57
	v_mul_f32_e32 v57, 0xbfb8aa3b, v57
	v_exp_f32_e32 v38, v38
	v_exp_f32_e32 v58, v58
	v_exp_f32_e32 v39, v39
	v_mul_f32_e32 v48, v48, v40
	v_mul_f32_e32 v40, 0xbfb8aa3b, v40
	v_exp_f32_e32 v57, v57
	v_exp_f32_e32 v40, v40
	v_add_f32_e32 v38, 1.0, v38
	v_add_f32_e32 v58, 1.0, v58
	v_add_f32_e32 v39, 1.0, v39
	v_add_f32_e32 v57, 1.0, v57
	v_rcp_f32_e32 v38, v38
	v_rcp_f32_e32 v58, v58
	v_rcp_f32_e32 v39, v39
	v_mul_f32_e32 v56, v56, v59
	v_mul_f32_e32 v59, 0xbfb8aa3b, v59
	v_add_f32_e32 v40, 1.0, v40
	v_rcp_f32_e32 v57, v57
	v_exp_f32_e32 v59, v59
	v_rcp_f32_e32 v40, v40
	v_mul_f32_e32 v38, v38, v46
	v_mul_f32_e32 v46, v58, v55
	v_mul_f32_e32 v39, v39, v47
	v_mul_f32_e32 v54, v57, v54
	v_cvt_pk_bf16_f32 v38, v54, v38
	v_cvt_pk_bf16_f32 v39, v46, v39
	v_lshlrev_b32_e32 v46, 16, v41
	v_add_f32_e32 v59, 1.0, v59
	v_mul_f32_e32 v40, v40, v48
	v_mul_f32_e32 v48, 0xbfb8aa3b, v46
	v_rcp_f32_e32 v59, v59
	v_exp_f32_e32 v48, v48
	v_and_b32_e32 v41, 0xffff0000, v41
	v_mul_f32_e32 v54, 0xbfb8aa3b, v41
	v_exp_f32_e32 v54, v54
	v_mul_f32_e32 v47, v59, v56
	v_add_f32_e32 v48, 1.0, v48
	v_cvt_pk_bf16_f32 v40, v47, v40
	v_lshlrev_b32_e32 v47, 16, v49
	v_rcp_f32_e32 v48, v48
	v_mul_f32_e32 v46, v47, v46
	v_add_f32_e32 v47, 1.0, v54
	v_rcp_f32_e32 v47, v47
	v_mul_f32_e32 v46, v48, v46
	v_and_b32_e32 v48, 0xffff0000, v49
	v_mul_f32_e32 v41, v48, v41
	v_mul_f32_e32 v41, v47, v41
	v_cvt_pk_bf16_f32 v41, v46, v41
	global_store_dwordx4 v[50:51], v[38:41], off nt
	ds_read_b128 v[46:49], v0 offset:1088
	s_waitcnt vmcnt(15)
; DI unsigned cvtpk(float lo, float hi) { unsigned r; asm volatile("v_cvt_pk_bf16_f32 %0, %1, %2" : "=v"(r) : "v"(lo), "v"(hi)); return r; }
; DI float bflo(unsigned w) { return __uint_as_float(w << 16); }
; DI float bfhi(unsigned w) { return __uint_as_float(w & 0xffff0000u); }
; DI float sigm(float x) { return rcpf_(1.f + ex2(-x * LOG2E)); }
; DI void attn_item(const bf16_t* __restrict__ Qw_, const bf16_t* __restrict__ Kh, const bf16_t* __restrict__ Vh, const bf16_t* Gw, bf16_t* Ow,
;                   int NT, int kt0, int qw, float sinkv, char* lds) {
;     ...
; #pragma unroll
;     for (int k = 0; k < 8; ++k) {
;         const u32x4 ov = *(const u32x4*)(OT + (er + 4 * k) * 136 + ec * 8); u32x4 w;
; #pragma unroll
;         for (int i = 0; i < 4; ++i) { const float g0 = bflo(gv[k][i]), g1 = bfhi(gv[k][i]); w[i] = cvtpk(bflo(ov[i]) * g0 * sigm(g0), bfhi(ov[i]) * g1 * sigm(g1)); }
;         __builtin_nontemporal_store(w, (u32x4*)(Ow + (size_t)(er + 4 * k) * 2048 + ec * 8));
;     }
	v_lshlrev_b32_e32 v38, 16, v42
	v_mul_f32_e32 v40, 0xbfb8aa3b, v38
	v_exp_f32_e32 v40, v40
	v_and_b32_e32 v41, 0xffff0000, v42
	v_mul_f32_e32 v42, 0xbfb8aa3b, v41
	v_exp_f32_e32 v42, v42
	v_add_f32_e32 v40, 1.0, v40
	s_waitcnt lgkmcnt(0)
	v_lshlrev_b32_e32 v39, 16, v46
	v_rcp_f32_e32 v40, v40
	v_mul_f32_e32 v38, v39, v38
	v_add_f32_e32 v39, 1.0, v42
	v_rcp_f32_e32 v39, v39
	v_mul_f32_e32 v38, v40, v38
	v_and_b32_e32 v40, 0xffff0000, v46
	v_mul_f32_e32 v40, v40, v41
	v_mul_f32_e32 v39, v39, v40
	v_cvt_pk_bf16_f32 v38, v38, v39
	v_lshlrev_b32_e32 v39, 16, v43
	v_mul_f32_e32 v41, 0xbfb8aa3b, v39
	v_exp_f32_e32 v41, v41
	v_and_b32_e32 v42, 0xffff0000, v43
	v_mul_f32_e32 v43, 0xbfb8aa3b, v42
	v_exp_f32_e32 v43, v43
	v_add_f32_e32 v41, 1.0, v41
	v_lshlrev_b32_e32 v40, 16, v47
	v_rcp_f32_e32 v41, v41
	v_mul_f32_e32 v39, v40, v39
	v_add_f32_e32 v40, 1.0, v43
	v_rcp_f32_e32 v40, v40
	v_mul_f32_e32 v39, v41, v39
	v_and_b32_e32 v41, 0xffff0000, v47
	v_mul_f32_e32 v41, v41, v42
	v_mul_f32_e32 v40, v40, v41
	v_cvt_pk_bf16_f32 v39, v39, v40
	v_lshlrev_b32_e32 v40, 16, v44
	v_mul_f32_e32 v42, 0xbfb8aa3b, v40
	v_exp_f32_e32 v42, v42
	v_and_b32_e32 v43, 0xffff0000, v44
	v_mul_f32_e32 v44, 0xbfb8aa3b, v43
	v_exp_f32_e32 v44, v44
	v_add_f32_e32 v42, 1.0, v42
	v_lshlrev_b32_e32 v41, 16, v48
	v_rcp_f32_e32 v42, v42
	v_mul_f32_e32 v40, v41, v40
	v_add_f32_e32 v41, 1.0, v44
	v_rcp_f32_e32 v41, v41
	v_mul_f32_e32 v40, v42, v40
	v_and_b32_e32 v42, 0xffff0000, v48
	v_mul_f32_e32 v42, v42, v43
	v_mul_f32_e32 v41, v41, v42
	v_cvt_pk_bf16_f32 v40, v40, v41
	v_lshlrev_b32_e32 v41, 16, v45
	v_mul_f32_e32 v43, 0xbfb8aa3b, v41
	v_exp_f32_e32 v43, v43
	v_and_b32_e32 v44, 0xffff0000, v45
	v_mul_f32_e32 v45, 0xbfb8aa3b, v44
	v_exp_f32_e32 v45, v45
	v_add_f32_e32 v43, 1.0, v43
	v_lshlrev_b32_e32 v42, 16, v49
	v_rcp_f32_e32 v43, v43
	v_mul_f32_e32 v41, v42, v41
	v_add_f32_e32 v42, 1.0, v45
	v_rcp_f32_e32 v42, v42
	v_mul_f32_e32 v41, v43, v41
	v_and_b32_e32 v43, 0xffff0000, v49
	v_mul_f32_e32 v43, v43, v44
	v_mul_f32_e32 v42, v42, v43
	v_cvt_pk_bf16_f32 v41, v41, v42
	global_store_dwordx4 v[52:53], v[38:41], off nt
	ds_read_b128 v[42:45], v0 offset:2176
	s_waitcnt vmcnt(15)
	v_lshlrev_b32_e32 v38, 16, v22
	v_mul_f32_e32 v40, 0xbfb8aa3b, v38
	v_exp_f32_e32 v40, v40
	v_and_b32_e32 v22, 0xffff0000, v22
	v_mul_f32_e32 v41, 0xbfb8aa3b, v22
	v_exp_f32_e32 v41, v41
	v_add_f32_e32 v40, 1.0, v40
	s_waitcnt lgkmcnt(0)
	v_lshlrev_b32_e32 v39, 16, v42
	v_rcp_f32_e32 v40, v40
	v_mul_f32_e32 v38, v39, v38
	v_add_f32_e32 v39, 1.0, v41
	v_rcp_f32_e32 v39, v39
	v_mul_f32_e32 v38, v40, v38
	v_and_b32_e32 v40, 0xffff0000, v42
	v_mul_f32_e32 v22, v40, v22
	v_mul_f32_e32 v22, v39, v22
	v_cvt_pk_bf16_f32 v22, v38, v22
	v_lshlrev_b32_e32 v38, 16, v23
	v_mul_f32_e32 v40, 0xbfb8aa3b, v38
	v_exp_f32_e32 v40, v40
	v_and_b32_e32 v23, 0xffff0000, v23
	v_mul_f32_e32 v41, 0xbfb8aa3b, v23
	v_exp_f32_e32 v41, v41
	v_add_f32_e32 v40, 1.0, v40
	v_lshlrev_b32_e32 v39, 16, v43
	v_rcp_f32_e32 v40, v40
	v_mul_f32_e32 v38, v39, v38
	v_add_f32_e32 v39, 1.0, v41
	v_rcp_f32_e32 v39, v39
	v_mul_f32_e32 v38, v40, v38
	v_and_b32_e32 v40, 0xffff0000, v43
	v_mul_f32_e32 v23, v40, v23
	v_mul_f32_e32 v23, v39, v23
	v_cvt_pk_bf16_f32 v23, v38, v23
	v_lshlrev_b32_e32 v38, 16, v24
	v_mul_f32_e32 v40, 0xbfb8aa3b, v38
	v_exp_f32_e32 v40, v40
	v_and_b32_e32 v24, 0xffff0000, v24
	v_mul_f32_e32 v41, 0xbfb8aa3b, v24
	v_exp_f32_e32 v41, v41
	v_add_f32_e32 v40, 1.0, v40
	v_lshlrev_b32_e32 v39, 16, v44
	v_rcp_f32_e32 v40, v40
	v_mul_f32_e32 v38, v39, v38
	v_add_f32_e32 v39, 1.0, v41
	v_rcp_f32_e32 v39, v39
	v_mul_f32_e32 v38, v40, v38
	v_and_b32_e32 v40, 0xffff0000, v44
	v_mul_f32_e32 v24, v40, v24
	v_mul_f32_e32 v24, v39, v24
	v_cvt_pk_bf16_f32 v24, v38, v24
	v_lshlrev_b32_e32 v38, 16, v25
	v_mul_f32_e32 v40, 0xbfb8aa3b, v38
	v_exp_f32_e32 v40, v40
	v_and_b32_e32 v25, 0xffff0000, v25
	v_mul_f32_e32 v41, 0xbfb8aa3b, v25
	v_exp_f32_e32 v41, v41
	v_add_f32_e32 v40, 1.0, v40
	v_lshlrev_b32_e32 v39, 16, v45
	v_rcp_f32_e32 v40, v40
	v_mul_f32_e32 v38, v39, v38
	v_add_f32_e32 v39, 1.0, v41
	v_rcp_f32_e32 v39, v39
	v_mul_f32_e32 v38, v40, v38
	v_and_b32_e32 v40, 0xffff0000, v45
	v_mul_f32_e32 v25, v40, v25
	v_mul_f32_e32 v25, v39, v25
	v_cvt_pk_bf16_f32 v25, v38, v25
	global_store_dwordx4 v[36:37], v[22:25], off nt
	ds_read_b128 v[38:41], v0 offset:3264
	s_waitcnt vmcnt(15)
	v_lshlrev_b32_e32 v22, 16, v18
	v_mul_f32_e32 v24, 0xbfb8aa3b, v22
	v_exp_f32_e32 v24, v24
	v_and_b32_e32 v18, 0xffff0000, v18
	v_mul_f32_e32 v25, 0xbfb8aa3b, v18
	v_exp_f32_e32 v25, v25
	v_add_f32_e32 v24, 1.0, v24
	s_waitcnt lgkmcnt(0)
	v_lshlrev_b32_e32 v23, 16, v38
	v_rcp_f32_e32 v24, v24
	v_mul_f32_e32 v22, v23, v22
	v_add_f32_e32 v23, 1.0, v25
	v_rcp_f32_e32 v23, v23
	v_mul_f32_e32 v22, v24, v22
	v_and_b32_e32 v24, 0xffff0000, v38
	v_mul_f32_e32 v18, v24, v18
	v_mul_f32_e32 v18, v23, v18
	v_cvt_pk_bf16_f32 v18, v22, v18
	v_lshlrev_b32_e32 v22, 16, v19
	v_mul_f32_e32 v24, 0xbfb8aa3b, v22
	v_exp_f32_e32 v24, v24
	v_and_b32_e32 v19, 0xffff0000, v19
	v_mul_f32_e32 v25, 0xbfb8aa3b, v19
	v_exp_f32_e32 v25, v25
	v_add_f32_e32 v24, 1.0, v24
	v_lshlrev_b32_e32 v23, 16, v39
	v_rcp_f32_e32 v24, v24
	v_mul_f32_e32 v22, v23, v22
	v_add_f32_e32 v23, 1.0, v25
	v_rcp_f32_e32 v23, v23
	v_mul_f32_e32 v22, v24, v22
	v_and_b32_e32 v24, 0xffff0000, v39
	v_mul_f32_e32 v19, v24, v19
	v_mul_f32_e32 v19, v23, v19
	v_cvt_pk_bf16_f32 v19, v22, v19
	v_lshlrev_b32_e32 v22, 16, v20
	v_mul_f32_e32 v24, 0xbfb8aa3b, v22
	v_exp_f32_e32 v24, v24
	v_and_b32_e32 v20, 0xffff0000, v20
	v_mul_f32_e32 v25, 0xbfb8aa3b, v20
	v_exp_f32_e32 v25, v25
	v_add_f32_e32 v24, 1.0, v24
	v_lshlrev_b32_e32 v23, 16, v40
	v_rcp_f32_e32 v24, v24
	v_mul_f32_e32 v22, v23, v22
	v_add_f32_e32 v23, 1.0, v25
	v_rcp_f32_e32 v23, v23
	v_mul_f32_e32 v22, v24, v22
	v_and_b32_e32 v24, 0xffff0000, v40
	v_mul_f32_e32 v20, v24, v20
	v_mul_f32_e32 v20, v23, v20
	v_cvt_pk_bf16_f32 v20, v22, v20
	v_lshlrev_b32_e32 v22, 16, v21
	v_mul_f32_e32 v24, 0xbfb8aa3b, v22
	v_exp_f32_e32 v24, v24
	v_and_b32_e32 v21, 0xffff0000, v21
	v_mul_f32_e32 v25, 0xbfb8aa3b, v21
	v_exp_f32_e32 v25, v25
	v_add_f32_e32 v24, 1.0, v24
	v_lshlrev_b32_e32 v23, 16, v41
	v_rcp_f32_e32 v24, v24
	v_mul_f32_e32 v22, v23, v22
	v_add_f32_e32 v23, 1.0, v25
	v_rcp_f32_e32 v23, v23
	v_mul_f32_e32 v22, v24, v22
	v_and_b32_e32 v24, 0xffff0000, v41
	v_mul_f32_e32 v21, v24, v21
	v_mul_f32_e32 v21, v23, v21
	v_cvt_pk_bf16_f32 v21, v22, v21
	global_store_dwordx4 v[34:35], v[18:21], off nt
	ds_read_b128 v[22:25], v0 offset:4352
	s_waitcnt vmcnt(15)
; DI unsigned cvtpk(float lo, float hi) { unsigned r; asm volatile("v_cvt_pk_bf16_f32 %0, %1, %2" : "=v"(r) : "v"(lo), "v"(hi)); return r; }
; DI float bflo(unsigned w) { return __uint_as_float(w << 16); }
; DI float bfhi(unsigned w) { return __uint_as_float(w & 0xffff0000u); }
; DI float sigm(float x) { return rcpf_(1.f + ex2(-x * LOG2E)); }
; DI void attn_item(const bf16_t* __restrict__ Qw_, const bf16_t* __restrict__ Kh, const bf16_t* __restrict__ Vh, const bf16_t* Gw, bf16_t* Ow,
;                   int NT, int kt0, int qw, float sinkv, char* lds) {
;     ...
; #pragma unroll
;     for (int k = 0; k < 8; ++k) {
;         const u32x4 ov = *(const u32x4*)(OT + (er + 4 * k) * 136 + ec * 8); u32x4 w;
; #pragma unroll
;         for (int i = 0; i < 4; ++i) { const float g0 = bflo(gv[k][i]), g1 = bfhi(gv[k][i]); w[i] = cvtpk(bflo(ov[i]) * g0 * sigm(g0), bfhi(ov[i]) * g1 * sigm(g1)); }
;         __builtin_nontemporal_store(w, (u32x4*)(Ow + (size_t)(er + 4 * k) * 2048 + ec * 8));
;     }
	v_lshlrev_b32_e32 v18, 16, v14
	v_mul_f32_e32 v20, 0xbfb8aa3b, v18
	v_exp_f32_e32 v20, v20
	v_and_b32_e32 v14, 0xffff0000, v14
	v_mul_f32_e32 v21, 0xbfb8aa3b, v14
	v_exp_f32_e32 v21, v21
	v_add_f32_e32 v20, 1.0, v20
	s_waitcnt lgkmcnt(0)
	v_lshlrev_b32_e32 v19, 16, v22
	v_rcp_f32_e32 v20, v20
	v_mul_f32_e32 v18, v19, v18
	v_add_f32_e32 v19, 1.0, v21
	v_rcp_f32_e32 v19, v19
	v_mul_f32_e32 v18, v20, v18
	v_and_b32_e32 v20, 0xffff0000, v22
	v_mul_f32_e32 v14, v20, v14
	v_mul_f32_e32 v14, v19, v14
	v_cvt_pk_bf16_f32 v14, v18, v14
	v_lshlrev_b32_e32 v18, 16, v15
	v_mul_f32_e32 v20, 0xbfb8aa3b, v18
	v_exp_f32_e32 v20, v20
	v_and_b32_e32 v15, 0xffff0000, v15
	v_mul_f32_e32 v21, 0xbfb8aa3b, v15
	v_exp_f32_e32 v21, v21
	v_add_f32_e32 v20, 1.0, v20
	v_lshlrev_b32_e32 v19, 16, v23
	v_rcp_f32_e32 v20, v20
	v_mul_f32_e32 v18, v19, v18
	v_add_f32_e32 v19, 1.0, v21
	v_rcp_f32_e32 v19, v19
	v_mul_f32_e32 v18, v20, v18
	v_and_b32_e32 v20, 0xffff0000, v23
	v_mul_f32_e32 v15, v20, v15
	v_mul_f32_e32 v15, v19, v15
	v_cvt_pk_bf16_f32 v15, v18, v15
	v_lshlrev_b32_e32 v18, 16, v16
	v_mul_f32_e32 v20, 0xbfb8aa3b, v18
	v_exp_f32_e32 v20, v20
	v_and_b32_e32 v16, 0xffff0000, v16
	v_mul_f32_e32 v21, 0xbfb8aa3b, v16
	v_exp_f32_e32 v21, v21
	v_add_f32_e32 v20, 1.0, v20
	v_lshlrev_b32_e32 v19, 16, v24
	v_rcp_f32_e32 v20, v20
	v_mul_f32_e32 v18, v19, v18
	v_add_f32_e32 v19, 1.0, v21
	v_rcp_f32_e32 v19, v19
	v_mul_f32_e32 v18, v20, v18
	v_and_b32_e32 v20, 0xffff0000, v24
	v_mul_f32_e32 v16, v20, v16
	v_mul_f32_e32 v16, v19, v16
	v_cvt_pk_bf16_f32 v16, v18, v16
	v_lshlrev_b32_e32 v18, 16, v17
	v_mul_f32_e32 v20, 0xbfb8aa3b, v18
	v_exp_f32_e32 v20, v20
	v_and_b32_e32 v17, 0xffff0000, v17
	v_mul_f32_e32 v21, 0xbfb8aa3b, v17
	v_exp_f32_e32 v21, v21
	v_add_f32_e32 v20, 1.0, v20
	v_lshlrev_b32_e32 v19, 16, v25
	v_rcp_f32_e32 v20, v20
	v_mul_f32_e32 v18, v19, v18
	v_add_f32_e32 v19, 1.0, v21
	v_rcp_f32_e32 v19, v19
	v_mul_f32_e32 v18, v20, v18
	v_and_b32_e32 v20, 0xffff0000, v25
	v_mul_f32_e32 v17, v20, v17
	v_mul_f32_e32 v17, v19, v17
	v_cvt_pk_bf16_f32 v17, v18, v17
	global_store_dwordx4 v[32:33], v[14:17], off nt
	ds_read_b128 v[18:21], v0 offset:5440
	s_waitcnt vmcnt(15)
	v_lshlrev_b32_e32 v14, 16, v10
	v_mul_f32_e32 v16, 0xbfb8aa3b, v14
	v_exp_f32_e32 v16, v16
	v_and_b32_e32 v10, 0xffff0000, v10
	v_mul_f32_e32 v17, 0xbfb8aa3b, v10
	v_exp_f32_e32 v17, v17
	v_add_f32_e32 v16, 1.0, v16
	s_waitcnt lgkmcnt(0)
	v_lshlrev_b32_e32 v15, 16, v18
	v_rcp_f32_e32 v16, v16
	v_mul_f32_e32 v14, v15, v14
	v_add_f32_e32 v15, 1.0, v17
	v_rcp_f32_e32 v15, v15
	v_mul_f32_e32 v14, v16, v14
	v_and_b32_e32 v16, 0xffff0000, v18
	v_mul_f32_e32 v10, v16, v10
	v_mul_f32_e32 v10, v15, v10
	v_cvt_pk_bf16_f32 v10, v14, v10
	v_lshlrev_b32_e32 v14, 16, v11
	v_mul_f32_e32 v16, 0xbfb8aa3b, v14
	v_exp_f32_e32 v16, v16
	v_and_b32_e32 v11, 0xffff0000, v11
	v_mul_f32_e32 v17, 0xbfb8aa3b, v11
	v_exp_f32_e32 v17, v17
	v_add_f32_e32 v16, 1.0, v16
	v_lshlrev_b32_e32 v15, 16, v19
	v_rcp_f32_e32 v16, v16
	v_mul_f32_e32 v14, v15, v14
	v_add_f32_e32 v15, 1.0, v17
	v_rcp_f32_e32 v15, v15
	v_mul_f32_e32 v14, v16, v14
	v_and_b32_e32 v16, 0xffff0000, v19
	v_mul_f32_e32 v11, v16, v11
	v_mul_f32_e32 v11, v15, v11
	v_cvt_pk_bf16_f32 v11, v14, v11
	v_lshlrev_b32_e32 v14, 16, v12
	v_mul_f32_e32 v16, 0xbfb8aa3b, v14
	v_exp_f32_e32 v16, v16
	v_and_b32_e32 v12, 0xffff0000, v12
	v_mul_f32_e32 v17, 0xbfb8aa3b, v12
	v_exp_f32_e32 v17, v17
	v_add_f32_e32 v16, 1.0, v16
	v_lshlrev_b32_e32 v15, 16, v20
	v_rcp_f32_e32 v16, v16
	v_mul_f32_e32 v14, v15, v14
	v_add_f32_e32 v15, 1.0, v17
	v_rcp_f32_e32 v15, v15
	v_mul_f32_e32 v14, v16, v14
	v_and_b32_e32 v16, 0xffff0000, v20
	v_mul_f32_e32 v12, v16, v12
	v_mul_f32_e32 v12, v15, v12
	v_cvt_pk_bf16_f32 v12, v14, v12
	v_lshlrev_b32_e32 v14, 16, v13
	v_mul_f32_e32 v16, 0xbfb8aa3b, v14
	v_exp_f32_e32 v16, v16
	v_and_b32_e32 v13, 0xffff0000, v13
	v_mul_f32_e32 v17, 0xbfb8aa3b, v13
	v_exp_f32_e32 v17, v17
	v_add_f32_e32 v16, 1.0, v16
	v_lshlrev_b32_e32 v15, 16, v21
	v_rcp_f32_e32 v16, v16
	v_mul_f32_e32 v14, v15, v14
	v_add_f32_e32 v15, 1.0, v17
	v_rcp_f32_e32 v15, v15
	v_mul_f32_e32 v14, v16, v14
	v_and_b32_e32 v16, 0xffff0000, v21
	v_mul_f32_e32 v13, v16, v13
	v_mul_f32_e32 v13, v15, v13
	v_cvt_pk_bf16_f32 v13, v14, v13
	global_store_dwordx4 v[30:31], v[10:13], off nt
	ds_read_b128 v[14:17], v0 offset:6528
	s_waitcnt vmcnt(15)
	v_lshlrev_b32_e32 v10, 16, v6
	v_mul_f32_e32 v12, 0xbfb8aa3b, v10
	v_exp_f32_e32 v12, v12
	v_and_b32_e32 v6, 0xffff0000, v6
	v_mul_f32_e32 v13, 0xbfb8aa3b, v6
	v_exp_f32_e32 v13, v13
	v_add_f32_e32 v12, 1.0, v12
	s_waitcnt lgkmcnt(0)
	v_lshlrev_b32_e32 v11, 16, v14
	v_rcp_f32_e32 v12, v12
	v_mul_f32_e32 v10, v11, v10
	v_add_f32_e32 v11, 1.0, v13
	v_rcp_f32_e32 v11, v11
	v_mul_f32_e32 v10, v12, v10
	v_and_b32_e32 v12, 0xffff0000, v14
	v_mul_f32_e32 v6, v12, v6
	v_mul_f32_e32 v6, v11, v6
	v_cvt_pk_bf16_f32 v6, v10, v6
	v_lshlrev_b32_e32 v10, 16, v7
	v_mul_f32_e32 v12, 0xbfb8aa3b, v10
	v_exp_f32_e32 v12, v12
	v_and_b32_e32 v7, 0xffff0000, v7
	v_mul_f32_e32 v13, 0xbfb8aa3b, v7
	v_exp_f32_e32 v13, v13
	v_add_f32_e32 v12, 1.0, v12
	v_lshlrev_b32_e32 v11, 16, v15
	v_rcp_f32_e32 v12, v12
	v_mul_f32_e32 v10, v11, v10
	v_add_f32_e32 v11, 1.0, v13
	v_rcp_f32_e32 v11, v11
	v_mul_f32_e32 v10, v12, v10
	v_and_b32_e32 v12, 0xffff0000, v15
	v_mul_f32_e32 v7, v12, v7
	v_mul_f32_e32 v7, v11, v7
	v_cvt_pk_bf16_f32 v7, v10, v7
	v_lshlrev_b32_e32 v10, 16, v8
	v_mul_f32_e32 v12, 0xbfb8aa3b, v10
	v_exp_f32_e32 v12, v12
	v_and_b32_e32 v8, 0xffff0000, v8
	v_mul_f32_e32 v13, 0xbfb8aa3b, v8
	v_exp_f32_e32 v13, v13
	v_add_f32_e32 v12, 1.0, v12
	v_lshlrev_b32_e32 v11, 16, v16
	v_rcp_f32_e32 v12, v12
	v_mul_f32_e32 v10, v11, v10
	v_add_f32_e32 v11, 1.0, v13
	v_rcp_f32_e32 v11, v11
	v_mul_f32_e32 v10, v12, v10
	v_and_b32_e32 v12, 0xffff0000, v16
	v_mul_f32_e32 v8, v12, v8
	v_mul_f32_e32 v8, v11, v8
	v_cvt_pk_bf16_f32 v8, v10, v8
	v_lshlrev_b32_e32 v10, 16, v9
	v_mul_f32_e32 v12, 0xbfb8aa3b, v10
	v_exp_f32_e32 v12, v12
	v_and_b32_e32 v9, 0xffff0000, v9
	v_mul_f32_e32 v13, 0xbfb8aa3b, v9
	v_exp_f32_e32 v13, v13
	v_add_f32_e32 v12, 1.0, v12
	v_lshlrev_b32_e32 v11, 16, v17
	v_rcp_f32_e32 v12, v12
	v_mul_f32_e32 v10, v11, v10
	v_add_f32_e32 v11, 1.0, v13
	v_rcp_f32_e32 v11, v11
	v_mul_f32_e32 v10, v12, v10
	v_and_b32_e32 v12, 0xffff0000, v17
	v_mul_f32_e32 v9, v12, v9
	v_mul_f32_e32 v9, v11, v9
	v_cvt_pk_bf16_f32 v9, v10, v9
	ds_read_b128 v[10:13], v0 offset:7616
	s_waitcnt vmcnt(14)
; DI unsigned cvtpk(float lo, float hi) { unsigned r; asm volatile("v_cvt_pk_bf16_f32 %0, %1, %2" : "=v"(r) : "v"(lo), "v"(hi)); return r; }
; DI float bflo(unsigned w) { return __uint_as_float(w << 16); }
; DI float bfhi(unsigned w) { return __uint_as_float(w & 0xffff0000u); }
; DI float sigm(float x) { return rcpf_(1.f + ex2(-x * LOG2E)); }
; DI void attn_item(const bf16_t* __restrict__ Qw_, const bf16_t* __restrict__ Kh, const bf16_t* __restrict__ Vh, const bf16_t* Gw, bf16_t* Ow,
;                   int NT, int kt0, int qw, float sinkv, char* lds) {
;     ...
; #pragma unroll
;     for (int k = 0; k < 8; ++k) {
;         const u32x4 ov = *(const u32x4*)(OT + (er + 4 * k) * 136 + ec * 8); u32x4 w;
; #pragma unroll
;         for (int i = 0; i < 4; ++i) { const float g0 = bflo(gv[k][i]), g1 = bfhi(gv[k][i]); w[i] = cvtpk(bflo(ov[i]) * g0 * sigm(g0), bfhi(ov[i]) * g1 * sigm(g1)); }
;         __builtin_nontemporal_store(w, (u32x4*)(Ow + (size_t)(er + 4 * k) * 2048 + ec * 8));
;     }
; DI void phase_att(const Params& p, unsigned char* shm) {
;     ...
;     for (int it = blockIdx.x; it < 1024; it += gridDim.x) {
;         const int hp = it & 1, g = (it >> 1) & 3, n = it >> 3;
;         const int head = g * 4 + hp * 2 + (wid >> 2), qw = 32 * (wid & 3);
;         const int kfirst = n == 0 ? 0 : (n - 1) * 128, NT = (n == 0 || n == 127) ? 4 : 6, kt0 = kfirst - n * 128;
;         __syncthreads();
;         const size_t go = (size_t)(n * 128 + qw) * 2048 + head * 128;
;         att::attn_item(Z + (size_t)(n * 128 + qw) * 3072 + head * 128, Z + (size_t)kfirst * 3072 + 2048 + g * 128, Z + (size_t)kfirst * 3072 + 2560 + g * 128,
	v_lshlrev_b32_e32 v0, 16, v2
	global_store_dwordx4 v[28:29], v[6:9], off nt
	v_and_b32_e32 v2, 0xffff0000, v2
	s_nop 0
	v_mul_f32_e32 v7, 0xbfb8aa3b, v0
	v_exp_f32_e32 v7, v7
	v_mul_f32_e32 v8, 0xbfb8aa3b, v2
	v_exp_f32_e32 v8, v8
	s_waitcnt lgkmcnt(0)
	v_lshlrev_b32_e32 v6, 16, v10
	v_add_f32_e32 v7, 1.0, v7
	v_rcp_f32_e32 v7, v7
	v_mul_f32_e32 v0, v6, v0
	v_add_f32_e32 v6, 1.0, v8
	v_rcp_f32_e32 v6, v6
	v_mul_f32_e32 v0, v7, v0
	v_and_b32_e32 v7, 0xffff0000, v10
	v_mul_f32_e32 v2, v7, v2
	v_mul_f32_e32 v2, v6, v2
	v_cvt_pk_bf16_f32 v2, v0, v2
	v_lshlrev_b32_e32 v0, 16, v3
	v_mul_f32_e32 v7, 0xbfb8aa3b, v0
	v_exp_f32_e32 v7, v7
	v_and_b32_e32 v3, 0xffff0000, v3
	v_mul_f32_e32 v8, 0xbfb8aa3b, v3
	v_exp_f32_e32 v8, v8
	v_add_f32_e32 v7, 1.0, v7
	v_lshlrev_b32_e32 v6, 16, v11
	v_rcp_f32_e32 v7, v7
	v_mul_f32_e32 v0, v6, v0
	v_add_f32_e32 v6, 1.0, v8
	v_rcp_f32_e32 v6, v6
	v_mul_f32_e32 v0, v7, v0
	v_and_b32_e32 v7, 0xffff0000, v11
	v_mul_f32_e32 v3, v7, v3
	v_mul_f32_e32 v3, v6, v3
	v_cvt_pk_bf16_f32 v3, v0, v3
	v_lshlrev_b32_e32 v0, 16, v4
	v_mul_f32_e32 v7, 0xbfb8aa3b, v0
	v_exp_f32_e32 v7, v7
	v_and_b32_e32 v4, 0xffff0000, v4
	v_mul_f32_e32 v8, 0xbfb8aa3b, v4
	v_exp_f32_e32 v8, v8
	v_add_f32_e32 v7, 1.0, v7
	v_lshlrev_b32_e32 v6, 16, v12
	v_rcp_f32_e32 v7, v7
	v_mul_f32_e32 v0, v6, v0
	v_add_f32_e32 v6, 1.0, v8
	v_rcp_f32_e32 v6, v6
	v_mul_f32_e32 v0, v7, v0
	v_and_b32_e32 v7, 0xffff0000, v12
	v_mul_f32_e32 v4, v7, v4
	v_mul_f32_e32 v4, v6, v4
	v_cvt_pk_bf16_f32 v4, v0, v4
	v_lshlrev_b32_e32 v0, 16, v5
	v_mul_f32_e32 v7, 0xbfb8aa3b, v0
	v_exp_f32_e32 v7, v7
	v_and_b32_e32 v5, 0xffff0000, v5
	v_mul_f32_e32 v8, 0xbfb8aa3b, v5
	v_exp_f32_e32 v8, v8
	v_add_f32_e32 v7, 1.0, v7
	v_lshlrev_b32_e32 v6, 16, v13
	v_rcp_f32_e32 v7, v7
	v_mul_f32_e32 v0, v6, v0
	v_add_f32_e32 v6, 1.0, v8
	v_rcp_f32_e32 v6, v6
	v_mul_f32_e32 v0, v7, v0
	v_and_b32_e32 v7, 0xffff0000, v13
	v_mul_f32_e32 v5, v7, v5
	v_mul_f32_e32 v5, v6, v5
	v_cvt_pk_bf16_f32 v5, v0, v5
	global_store_dwordx4 v[26:27], v[2:5], off nt
	s_cbranch_scc0 .LBB0_265
.LBB0_238:
	s_lshl_b32 s5, s51, 1
	s_bfe_u32 s15, s51, 0x20001
	s_ashr_i32 s54, s51, 3
	s_and_b32 s5, s5, 2
	s_lshl_b32 s4, s15, 2
	s_add_i32 s17, s5, s31
	s_lshl_b32 s58, s54, 7
	s_add_i32 s17, s17, s4
	s_add_i32 s14, s58, 0xffffff80
	s_cmp_lt_u32 s51, 8
	s_cselect_b64 s[20:21], -1, 0
	s_and_b64 s[4:5], s[20:21], exec
	s_cselect_b32 s16, 0, s14
	s_or_b32 s14, s58, s34
	s_sub_i32 s55, s16, s58
	s_mul_i32 s5, s14, 0x1800
	s_mul_hi_i32 s4, s14, 0x1800
	s_add_u32 s5, s11, s5
	s_addc_u32 s4, s22, s4
	s_lshl_b32 s18, s17, 8
	s_add_u32 s52, s5, s18
	s_addc_u32 s53, s4, 0
	s_mul_i32 s5, s16, 0x1800
	s_mul_hi_i32 s4, s16, 0x1800
	s_add_u32 s5, s11, s5
	s_addc_u32 s4, s22, s4
	s_lshl_b32 s15, s15, 8
	s_add_u32 s15, s5, s15
	s_addc_u32 s19, s4, 0
	s_add_u32 s4, s15, 0x1000
	s_addc_u32 s5, s19, 0
	s_add_u32 s18, s15, 0x1400
	s_addc_u32 s19, s19, 0
	s_barrier
	global_load_dwordx4 v[2:5], v200, s[18:19]
	global_load_dwordx4 v[6:9], v201, s[18:19]
	global_load_dwordx4 v[10:13], v200, s[4:5]
	global_load_dwordx4 v[14:17], v201, s[4:5]
	s_cmp_eq_u32 s71, 1
	s_cbranch_scc1 .Latt_q_inflight
	v_lshl_add_u64 v[18:19], s[52:53], 0, v[178:179]
	v_lshl_add_u64 v[18:19], v[18:19], 0, v[184:185]
	global_load_dwordx4 v[126:129], v[18:19], off
	global_load_dwordx4 v[122:125], v[18:19], off offset:32
	global_load_dwordx4 v[118:121], v[18:19], off offset:64
	global_load_dwordx4 v[114:117], v[18:19], off offset:96
	global_load_dwordx4 v[110:113], v[18:19], off offset:128
	global_load_dwordx4 v[106:109], v[18:19], off offset:160
	global_load_dwordx4 v[102:105], v[18:19], off offset:192
	global_load_dwordx4 v[98:101], v[18:19], off offset:224
; DI void maskT(f32x16& p0, f32x16& p1, int kt, int qw, int r32, int hi) {
;     if ((kt - qw - 31 < -128) || (kt + 63 - qw > 128)) {
;         const int db = kt - (qw + r32) + 4 * hi;
; #pragma unroll
;         for (int r = 0; r < 16; ++r) { const int d = db + (r & 3) + 8 * (r >> 2);
;             p0[r] = (d >= -128 && d <= 128) ? p0[r] : -1e30f; p1[r] = (d + 32 >= -128 && d + 32 <= 128) ? p1[r] : -1e30f; }
;     }
; }
; DI void qkt(f32x16& p0, f32x16& p1, const char* Ks, const bf16x8* qr, int r32, int hi) {
; #pragma unroll
;     for (int i = 0; i < 16; ++i) { p0[i] = 0.f; p1[i] = 0.f; }
; #pragma unroll
;     for (int d0 = 0; d0 < 8; ++d0) { const int cb = (d0 * 16 + hi * 8) * 2;
;         const bf16x8 b0 = *reinterpret_cast<const bf16x8*>(Ks + KSWZ(r32, cb));
;         const bf16x8 b1 = *reinterpret_cast<const bf16x8*>(Ks + KSWZ(32 + r32, cb));
;         p0 = __builtin_amdgcn_mfma_f32_32x32x16_bf16(b0, qr[d0], p0, 0, 0, 0);
;         p1 = __builtin_amdgcn_mfma_f32_32x32x16_bf16(b1, qr[d0], p1, 0, 0, 0); }
; }
.Latt_q_inflight:
	s_lshl_b32 s15, s17, 2
	v_mov_b32_e32 v0, s15
	global_load_dword v0, v0, s[8:9]
	s_waitcnt vmcnt(0)
	s_cmp_lt_i32 s55, s37
	s_cselect_b64 s[56:57], -1, 0
	s_sub_i32 s15, s55, s34
	s_add_i32 s15, s15, 63
	s_cmpk_gt_i32 s15, 0x80
	s_cselect_b64 s[60:61], -1, 0
	s_or_b64 s[56:57], s[56:57], s[60:61]
	v_readfirstlane_b32 s52, v202
	s_andn2_b64 vcc, exec, s[56:57]
	s_waitcnt vmcnt(12)
	ds_write_b128 v208, v[2:5]
	s_waitcnt vmcnt(11)
	ds_write_b128 v209, v[6:9]
	s_waitcnt vmcnt(10)
	ds_write_b128 v210, v[10:13] offset:32768
	s_waitcnt vmcnt(9)
	ds_write_b128 v211, v[14:17] offset:32768
	s_waitcnt lgkmcnt(0)
	s_barrier
	ds_read_b128 v[2:5], v212 offset:32768
	ds_read_b128 v[6:9], v212 offset:40960
	s_waitcnt vmcnt(8) lgkmcnt(1)
	v_mfma_f32_32x32x16_bf16 v[18:33], v[2:5], v[126:129], 0
	ds_read_b128 v[34:37], v213 offset:32768
	ds_read_b128 v[38:41], v213 offset:40960
	s_waitcnt lgkmcnt(2)
	v_mfma_f32_32x32x16_bf16 v[2:17], v[6:9], v[126:129], 0
	s_waitcnt vmcnt(7) lgkmcnt(1)
	v_mfma_f32_32x32x16_bf16 v[18:33], v[34:37], v[122:125], v[18:33]
	s_waitcnt lgkmcnt(0)
	v_mfma_f32_32x32x16_bf16 v[2:17], v[38:41], v[122:125], v[2:17]
	ds_read_b128 v[34:37], v214 offset:32768
	ds_read_b128 v[38:41], v214 offset:40960
	s_waitcnt vmcnt(6) lgkmcnt(1)
	v_mfma_f32_32x32x16_bf16 v[18:33], v[34:37], v[118:121], v[18:33]
	s_waitcnt lgkmcnt(0)
	v_mfma_f32_32x32x16_bf16 v[2:17], v[38:41], v[118:121], v[2:17]
	ds_read_b128 v[34:37], v215 offset:32768
	ds_read_b128 v[38:41], v215 offset:40960
	s_waitcnt vmcnt(5) lgkmcnt(1)
	v_mfma_f32_32x32x16_bf16 v[18:33], v[34:37], v[114:117], v[18:33]
	s_waitcnt lgkmcnt(0)
	v_mfma_f32_32x32x16_bf16 v[2:17], v[38:41], v[114:117], v[2:17]
	ds_read_b128 v[34:37], v216 offset:32768
	ds_read_b128 v[38:41], v216 offset:40960
	s_waitcnt vmcnt(4) lgkmcnt(1)
	v_mfma_f32_32x32x16_bf16 v[18:33], v[34:37], v[110:113], v[18:33]
	s_waitcnt lgkmcnt(0)
	v_mfma_f32_32x32x16_bf16 v[2:17], v[38:41], v[110:113], v[2:17]
	ds_read_b128 v[34:37], v217 offset:32768
	ds_read_b128 v[38:41], v217 offset:40960
	s_waitcnt vmcnt(3) lgkmcnt(1)
	v_mfma_f32_32x32x16_bf16 v[18:33], v[34:37], v[106:109], v[18:33]
	s_waitcnt lgkmcnt(0)
	v_mfma_f32_32x32x16_bf16 v[2:17], v[38:41], v[106:109], v[2:17]
	ds_read_b128 v[34:37], v218 offset:32768
	ds_read_b128 v[38:41], v218 offset:40960
	s_waitcnt vmcnt(2) lgkmcnt(1)
	v_mfma_f32_32x32x16_bf16 v[18:33], v[34:37], v[102:105], v[18:33]
	ds_read_b128 v[34:37], v219 offset:32768
	s_waitcnt lgkmcnt(1)
	v_mfma_f32_32x32x16_bf16 v[2:17], v[38:41], v[102:105], v[2:17]
	ds_read_b128 v[38:41], v219 offset:40960
	s_waitcnt vmcnt(1) lgkmcnt(1)
	v_mfma_f32_32x32x16_bf16 v[18:33], v[34:37], v[98:101], v[18:33]
	s_waitcnt lgkmcnt(0)
	v_mfma_f32_32x32x16_bf16 v[2:17], v[38:41], v[98:101], v[2:17]
	s_cbranch_vccnz .LBB0_240
	v_or_b32_e32 v34, s55, v193
	v_sub_u32_e32 v34, v34, v192
	v_add_u32_e32 v35, 0x80, v34
	v_cmp_gt_u32_e32 vcc, s41, v35
	v_add_u32_e32 v35, 0xa0, v34
	s_nop 3
	v_cndmask_b32_e32 v18, v220, v18, vcc
	v_cmp_gt_u32_e32 vcc, s41, v35
	v_add_u32_e32 v35, 0x81, v34
	s_nop 0
	v_cndmask_b32_e32 v2, v220, v2, vcc
	v_cmp_gt_u32_e32 vcc, s41, v35
	v_add_u32_e32 v35, 0xa1, v34
	s_nop 0
	v_cndmask_b32_e32 v19, v220, v19, vcc
	v_cmp_gt_u32_e32 vcc, s41, v35
	v_add_u32_e32 v35, 0x82, v34
	s_nop 0
	v_cndmask_b32_e32 v3, v220, v3, vcc
	v_cmp_gt_u32_e32 vcc, s41, v35
	v_add_u32_e32 v35, 0xa2, v34
	s_nop 0
	v_cndmask_b32_e32 v20, v220, v20, vcc
	v_cmp_gt_u32_e32 vcc, s41, v35
	v_add_u32_e32 v35, 0x83, v34
	s_nop 0
	v_cndmask_b32_e32 v4, v220, v4, vcc
	v_cmp_gt_u32_e32 vcc, s41, v35
	v_add_u32_e32 v35, 0xa3, v34
	s_nop 0
	v_cndmask_b32_e32 v21, v220, v21, vcc
	v_cmp_gt_u32_e32 vcc, s41, v35
	v_add_u32_e32 v35, 0x88, v34
	s_nop 0
	v_cndmask_b32_e32 v5, v220, v5, vcc
	v_cmp_gt_u32_e32 vcc, s41, v35
	v_add_u32_e32 v35, 0xa8, v34
	s_nop 0
	v_cndmask_b32_e32 v22, v220, v22, vcc
	v_cmp_gt_u32_e32 vcc, s41, v35
	v_add_u32_e32 v35, 0x89, v34
	s_nop 0
	v_cndmask_b32_e32 v6, v220, v6, vcc
	v_cmp_gt_u32_e32 vcc, s41, v35
	v_add_u32_e32 v35, 0xa9, v34
	s_nop 0
	v_cndmask_b32_e32 v23, v220, v23, vcc
	v_cmp_gt_u32_e32 vcc, s41, v35
	v_add_u32_e32 v35, 0x8a, v34
	s_nop 0
	v_cndmask_b32_e32 v7, v220, v7, vcc
	v_cmp_gt_u32_e32 vcc, s41, v35
	v_add_u32_e32 v35, 0xaa, v34
	s_nop 0
	v_cndmask_b32_e32 v24, v220, v24, vcc
	v_cmp_gt_u32_e32 vcc, s41, v35
	v_add_u32_e32 v35, 0x8b, v34
	s_nop 0
	v_cndmask_b32_e32 v8, v220, v8, vcc
	v_cmp_gt_u32_e32 vcc, s41, v35
	v_add_u32_e32 v35, 0xab, v34
	s_nop 0
	v_cndmask_b32_e32 v25, v220, v25, vcc
	v_cmp_gt_u32_e32 vcc, s41, v35
	v_add_u32_e32 v35, 0x90, v34
	s_nop 0
	v_cndmask_b32_e32 v9, v220, v9, vcc
	v_cmp_gt_u32_e32 vcc, s41, v35
	v_add_u32_e32 v35, 0xb0, v34
	s_nop 0
	v_cndmask_b32_e32 v26, v220, v26, vcc
	v_cmp_gt_u32_e32 vcc, s41, v35
	v_add_u32_e32 v35, 0x91, v34
	s_nop 0
	v_cndmask_b32_e32 v10, v220, v10, vcc
	v_cmp_gt_u32_e32 vcc, s41, v35
	v_add_u32_e32 v35, 0xb1, v34
	s_nop 0
	v_cndmask_b32_e32 v27, v220, v27, vcc
	v_cmp_gt_u32_e32 vcc, s41, v35
	v_add_u32_e32 v35, 0x92, v34
	s_nop 0
	v_cndmask_b32_e32 v11, v220, v11, vcc
	v_cmp_gt_u32_e32 vcc, s41, v35
	v_add_u32_e32 v35, 0xb2, v34
	s_nop 0
	v_cndmask_b32_e32 v28, v220, v28, vcc
	v_cmp_gt_u32_e32 vcc, s41, v35
	v_add_u32_e32 v35, 0x93, v34
	s_nop 0
	v_cndmask_b32_e32 v12, v220, v12, vcc
	v_cmp_gt_u32_e32 vcc, s41, v35
	v_add_u32_e32 v35, 0xb3, v34
	s_nop 0
	v_cndmask_b32_e32 v29, v220, v29, vcc
	v_cmp_gt_u32_e32 vcc, s41, v35
	v_add_u32_e32 v35, 0x98, v34
	s_nop 0
	v_cndmask_b32_e32 v13, v220, v13, vcc
	v_cmp_gt_u32_e32 vcc, s41, v35
	v_add_u32_e32 v35, 0xb8, v34
	s_nop 0
	v_cndmask_b32_e32 v30, v220, v30, vcc
	v_cmp_gt_u32_e32 vcc, s41, v35
	v_add_u32_e32 v35, 0x99, v34
	s_nop 0
	v_cndmask_b32_e32 v14, v220, v14, vcc
	v_cmp_gt_u32_e32 vcc, s41, v35
	v_add_u32_e32 v35, 0xb9, v34
	s_nop 0
	v_cndmask_b32_e32 v31, v220, v31, vcc
	v_cmp_gt_u32_e32 vcc, s41, v35
	v_add_u32_e32 v35, 0x9a, v34
	s_nop 0
	v_cndmask_b32_e32 v15, v220, v15, vcc
	v_cmp_gt_u32_e32 vcc, s41, v35
	v_add_u32_e32 v35, 0xba, v34
	s_nop 0
	v_cndmask_b32_e32 v32, v220, v32, vcc
	v_cmp_gt_u32_e32 vcc, s41, v35
	v_add_u32_e32 v35, 0x9b, v34
	v_add_u32_e32 v34, 0xbb, v34
	v_cndmask_b32_e32 v16, v220, v16, vcc
	v_cmp_gt_u32_e32 vcc, s41, v35
	s_nop 1
	v_cndmask_b32_e32 v33, v220, v33, vcc
	v_cmp_gt_u32_e32 vcc, s41, v34
	s_nop 1
	v_cndmask_b32_e32 v17, v220, v17, vcc
